# pass A scan token loop also moved to MFMA 32x32 state layout (P and Q via v_mfma_f32_32x32x2_f32, packed f32 dots), natural-layout P/Q store
# speedup vs baseline: 1.0236x; 1.0236x over previous
.LBB0_334:
	s_mul_i32 s6, s13, 0x4200
	s_add_i32 s18, s6, 0
	s_add_i32 s6, s12, -7
	s_and_b64 s[14:15], s[2:3], exec
	v_mbcnt_lo_u32_b32 v66, -1, 0
	s_cselect_b32 s12, s12, s6
	v_mbcnt_hi_u32_b32 v161, -1, v66
	s_add_i32 s6, s12, -1
	v_add_u32_e32 v66, s20, v161
	s_max_i32 s6, s6, s8
	v_mov_b32_e32 v69, 0
	v_lshlrev_b32_e32 v68, 1, v66
	s_min_i32 s6, s6, s9
	s_mov_b32 s7, 0
	v_lshl_add_u64 v[158:159], s[88:89], 0, v[68:69]
	s_mulk_i32 s6, 0x1800
	v_lshl_add_u64 v[70:71], v[158:159], 0, s[6:7]
	s_max_i32 s6, s12, s8
	s_min_i32 s6, s6, s9
	s_mulk_i32 s6, 0x1800
	v_lshl_add_u64 v[72:73], v[158:159], 0, s[6:7]
	s_add_i32 s6, s12, 1
	s_max_i32 s6, s6, s8
	s_min_i32 s6, s6, s9
	s_mulk_i32 s6, 0x1800
	v_lshl_add_u64 v[74:75], v[158:159], 0, s[6:7]
	s_add_i32 s6, s12, 2
	s_max_i32 s6, s6, s8
	s_min_i32 s6, s6, s9
	s_mulk_i32 s6, 0x1800
	v_lshl_add_u64 v[76:77], v[158:159], 0, s[6:7]
	s_add_i32 s6, s12, 3
	s_max_i32 s6, s6, s8
	s_min_i32 s6, s6, s9
	s_mulk_i32 s6, 0x1800
	v_lshl_add_u64 v[78:79], v[158:159], 0, s[6:7]
	s_add_i32 s6, s12, 4
	s_max_i32 s6, s6, s8
	s_min_i32 s6, s6, s9
	s_mulk_i32 s6, 0x1800
	v_lshl_add_u64 v[80:81], v[158:159], 0, s[6:7]
	s_add_i32 s6, s12, 5
	s_max_i32 s6, s6, s8
	s_min_i32 s6, s6, s9
	s_mulk_i32 s6, 0x1800
	v_lshl_add_u64 v[82:83], v[158:159], 0, s[6:7]
	s_add_i32 s6, s12, 6
	s_max_i32 s6, s6, s8
	s_min_i32 s6, s6, s9
	s_mulk_i32 s6, 0x1800
	v_lshl_add_u64 v[84:85], v[158:159], 0, s[6:7]
	s_add_i32 s6, s12, 7
	global_load_ushort v236, v[70:71], off
	global_load_ushort v233, v[72:73], off
	global_load_ushort v235, v[74:75], off
	global_load_ushort v232, v[76:77], off
	global_load_ushort v230, v[78:79], off
	global_load_ushort v229, v[80:81], off
	global_load_ushort v228, v[82:83], off
	global_load_ushort v227, v[84:85], off
	s_max_i32 s6, s6, s8
	s_min_i32 s6, s6, s9
	s_mulk_i32 s6, 0x1800
	s_add_i32 s12, s12, 8
	v_lshl_add_u64 v[70:71], v[158:159], 0, s[6:7]
	s_max_i32 s6, s12, s8
	s_min_i32 s6, s6, s9
	s_mulk_i32 s6, 0x1800
	v_lshl_add_u64 v[72:73], v[158:159], 0, s[6:7]
	global_load_ushort v234, v[70:71], off
	global_load_ushort v231, v[72:73], off
	v_cmp_eq_u32_e32 vcc, 0, v1
	s_add_i32 s6, 0, 0x25d00
	v_lshlrev_b32_e32 v71, 2, v161
	v_cndmask_b32_e64 v6, 0, 1.0, vcc
	v_cmp_eq_u32_e32 vcc, 1, v1
	v_add_u32_e32 v170, s6, v71
	s_add_i32 s6, 0, 0x25e00
	v_cndmask_b32_e64 v7, 0, 1.0, vcc
	v_cmp_eq_u32_e32 vcc, 2, v1
	v_add_u32_e32 v171, s6, v71
	s_and_b64 s[6:7], s[2:3], exec
	v_cndmask_b32_e64 v8, 0, 1.0, vcc
	v_cmp_eq_u32_e32 vcc, 3, v1
	v_lshl_add_u32 v67, s19, 6, v161
	s_cselect_b32 s8, 0, 7
	v_cndmask_b32_e64 v9, 0, 1.0, vcc
	v_cmp_eq_u32_e32 vcc, 4, v1
	s_cselect_b32 s12, 1, 6
	s_cselect_b32 s15, 2, 5
	v_cndmask_b32_e64 v2, 0, 1.0, vcc
	v_cmp_eq_u32_e32 vcc, 5, v1
	s_add_i32 s17, s19, 3
	s_sub_i32 s19, 4, s19
	v_cndmask_b32_e64 v3, 0, 1.0, vcc
	v_cmp_eq_u32_e32 vcc, 6, v1
	v_or_b32_e32 v70, 0x900, v67
	v_add_u32_e32 v72, 0x980, v67
	v_cndmask_b32_e64 v4, 0, 1.0, vcc
	v_cmp_eq_u32_e32 vcc, 7, v1
	v_and_b32_e32 v67, 15, v161
	v_lshrrev_b32_e32 v68, 4, v161
	v_cndmask_b32_e64 v5, 0, 1.0, vcc
	v_cmp_eq_u32_e32 vcc, 8, v1
	s_and_b64 s[6:7], s[2:3], exec
	v_lshlrev_b32_e32 v74, 2, v68
	v_cndmask_b32_e64 v10, 0, 1.0, vcc
	v_cmp_eq_u32_e32 vcc, 9, v1
	v_lshl_add_u32 v75, v67, 4, s18
	s_cselect_b32 s6, 5, 2
	v_cndmask_b32_e64 v11, 0, 1.0, vcc
	v_cmp_eq_u32_e32 vcc, 10, v1
	s_cselect_b32 s22, 6, 1
	s_cselect_b32 s24, 7, 0
	v_cndmask_b32_e64 v12, 0, 1.0, vcc
	v_cmp_eq_u32_e32 vcc, 11, v1
	v_add_u32_e32 v76, v75, v74
	s_mul_i32 s9, s8, 0x600
	v_cndmask_b32_e64 v13, 0, 1.0, vcc
	v_cmp_eq_u32_e32 vcc, 12, v1
	s_mul_i32 s14, s12, 0x600
	s_mul_i32 s16, s15, 0x600
	v_cndmask_b32_e64 v14, 0, 1.0, vcc
	v_cmp_eq_u32_e32 vcc, 13, v1
	s_mul_i32 s20, s17, 0x600
	s_mul_i32 s21, s19, 0x600
	v_cndmask_b32_e64 v15, 0, 1.0, vcc
	v_cmp_eq_u32_e32 vcc, 14, v1
	s_mul_i32 s7, s6, 0x600
	s_mul_i32 s23, s22, 0x600
	v_cndmask_b32_e64 v16, 0, 1.0, vcc
	v_cmp_eq_u32_e32 vcc, 15, v1
	s_mul_i32 s25, s24, 0x600
	v_add_u32_e32 v172, s9, v76
	v_cndmask_b32_e64 v17, 0, 1.0, vcc
	v_cmp_eq_u32_e32 vcc, 16, v1
	v_add_u32_e32 v173, s14, v76
	v_add_u32_e32 v174, s16, v76
	v_cndmask_b32_e64 v18, 0, 1.0, vcc
	v_cmp_eq_u32_e32 vcc, 17, v1
	v_add_u32_e32 v175, s20, v76
	v_add_u32_e32 v176, s21, v76
	v_cndmask_b32_e64 v19, 0, 1.0, vcc
	v_cmp_eq_u32_e32 vcc, 18, v1
	v_add_u32_e32 v177, s7, v76
	v_add_u32_e32 v178, s23, v76
	v_cndmask_b32_e64 v20, 0, 1.0, vcc
	v_cmp_eq_u32_e32 vcc, 19, v1
	v_add_u32_e32 v179, s25, v76
	v_add_u32_e32 v76, s18, v71
	v_cndmask_b32_e64 v21, 0, 1.0, vcc
	v_cmp_eq_u32_e32 vcc, 20, v1
	v_add_u32_e32 v187, s7, v76
	s_add_i32 s7, 0, 0x26400
	v_cndmask_b32_e64 v22, 0, 1.0, vcc
	v_cmp_eq_u32_e32 vcc, 21, v1
	s_mulk_i32 s8, 0x90
	v_add_u32_e32 v191, s7, v71
	v_cndmask_b32_e64 v23, 0, 1.0, vcc
	v_cmp_eq_u32_e32 vcc, 22, v1
	s_add_i32 s7, s18, s8
	v_lshlrev_b32_e32 v77, 1, v161
	v_cndmask_b32_e64 v24, 0, 1.0, vcc
	v_cmp_eq_u32_e32 vcc, 23, v1
	s_mulk_i32 s12, 0x90
	v_add_u32_e32 v192, s7, v77
	v_cndmask_b32_e64 v25, 0, 1.0, vcc
	v_cmp_eq_u32_e32 vcc, 24, v1
	s_add_i32 s7, s18, s12
	s_mulk_i32 s15, 0x90
	v_cndmask_b32_e64 v26, 0, 1.0, vcc
	v_cmp_eq_u32_e32 vcc, 25, v1
	v_add_u32_e32 v194, s7, v77
	s_add_i32 s7, s18, s15
	v_cndmask_b32_e64 v27, 0, 1.0, vcc
	v_cmp_eq_u32_e32 vcc, 26, v1
	s_mulk_i32 s17, 0x90
	v_add_u32_e32 v196, s7, v77
	v_cndmask_b32_e64 v28, 0, 1.0, vcc
	v_cmp_eq_u32_e32 vcc, 27, v1
	s_add_i32 s7, s18, s17
	s_mulk_i32 s19, 0x90
	v_cndmask_b32_e64 v29, 0, 1.0, vcc
	v_cmp_eq_u32_e32 vcc, 28, v1
	v_sub_u32_e32 v78, v76, v77
	v_add_u32_e32 v198, s7, v77
	v_cndmask_b32_e64 v30, 0, 1.0, vcc
	v_cmp_eq_u32_e32 vcc, 29, v1
	s_add_i32 s7, s18, s19
	s_mulk_i32 s6, 0x90
	v_cndmask_b32_e64 v31, 0, 1.0, vcc
	v_cmp_eq_u32_e32 vcc, 30, v1
	s_mulk_i32 s22, 0x90
	v_add_u32_e32 v200, s7, v77
	v_cndmask_b32_e64 v32, 0, 1.0, vcc
	v_cmp_eq_u32_e32 vcc, 31, v1
	s_add_i32 s7, s18, s6
	v_add_u32_e32 v203, s6, v78
	v_cndmask_b32_e64 v33, 0, 1.0, vcc
	v_cmp_eq_u32_e32 vcc, 32, v1
	s_add_i32 s6, s18, s22
	s_mulk_i32 s24, 0x90
	v_cndmask_b32_e64 v34, 0, 1.0, vcc
	v_cmp_eq_u32_e32 vcc, 33, v1
	s_add_i32 s26, 0, 0x26000
	v_add_u32_e32 v204, s6, v77
	v_cndmask_b32_e64 v35, 0, 1.0, vcc
	v_cmp_eq_u32_e32 vcc, 34, v1
	s_add_i32 s6, s18, s24
	v_lshlrev_b32_e32 v73, 2, v67
	v_cndmask_b32_e64 v36, 0, 1.0, vcc
	v_cmp_eq_u32_e32 vcc, 35, v1
	v_add_u32_e32 v180, s26, v71
	s_add_i32 s26, 0, 0x26200
	v_cndmask_b32_e64 v37, 0, 1.0, vcc
	v_cmp_eq_u32_e32 vcc, 36, v1
	v_add_u32_e32 v206, s6, v77
	s_add_i32 s6, 0, 0x26600
	v_cndmask_b32_e64 v38, 0, 1.0, vcc
	v_cmp_eq_u32_e32 vcc, 37, v1
	v_mul_u32_u24_e32 v67, 0x48, v67
	v_add_u32_e32 v181, s26, v71
	v_cndmask_b32_e64 v39, 0, 1.0, vcc
	v_cmp_eq_u32_e32 vcc, 38, v1
	v_add_u32_e32 v182, s9, v76
	v_add_u32_e32 v193, s8, v78
	v_cndmask_b32_e64 v40, 0, 1.0, vcc
	v_cmp_eq_u32_e32 vcc, 39, v1
	v_add_u32_e32 v208, s6, v71
	v_lshlrev_b32_e32 v67, 1, v67
	v_cndmask_b32_e64 v41, 0, 1.0, vcc
	v_cmp_eq_u32_e32 vcc, 40, v1
	v_and_b32_e32 v71, 0x70, v161
	s_add_i32 s8, 0, 0x21000
	v_cndmask_b32_e64 v42, 0, 1.0, vcc
	v_cmp_eq_u32_e32 vcc, 41, v1
	s_add_i32 s9, 0, 0x23400
	v_add3_u32 v210, s8, v71, v67
	v_cndmask_b32_e64 v43, 0, 1.0, vcc
	v_cmp_eq_u32_e32 vcc, 42, v1
	v_add3_u32 v211, s9, v71, v67
	v_cmp_lt_i32_e64 s[8:9], 1, v68
	v_cndmask_b32_e64 v44, 0, 1.0, vcc
	v_cmp_eq_u32_e32 vcc, 43, v1
	v_add3_u32 v209, s18, v67, v71
	v_cndmask_b32_e64 v67, 0, 2, s[8:9]
	v_cndmask_b32_e64 v45, 0, 1.0, vcc
	v_cmp_eq_u32_e32 vcc, 44, v1
	v_or_b32_e32 v68, v67, v73
	v_and_b32_e32 v71, 4, v74
	v_cndmask_b32_e64 v46, 0, 1.0, vcc
	v_cmp_eq_u32_e32 vcc, 45, v1
	v_add_u32_e32 v195, s12, v78
	v_lshlrev_b32_e32 v68, 2, v68
	v_cndmask_b32_e64 v47, 0, 1.0, vcc
	v_cmp_eq_u32_e32 vcc, 46, v1
	s_add_i32 s12, 0, 0x25800
	v_mul_u32_u24_e32 v71, 0x180, v71
	v_cndmask_b32_e64 v48, 0, 1.0, vcc
	v_cmp_eq_u32_e32 vcc, 47, v1
	v_add_u32_e32 v202, s7, v77
	v_add_u32_e32 v212, s12, v68
	v_cndmask_b32_e64 v49, 0, 1.0, vcc
	v_cmp_eq_u32_e32 vcc, 48, v1
	s_add_i32 s12, 0, 0x25900
	v_and_b32_e32 v77, 64, v161
	v_cndmask_b32_e64 v50, 0, 1.0, vcc
	v_cmp_eq_u32_e32 vcc, 49, v1
	v_lshlrev_b32_e32 v71, 2, v71
	v_add_u32_e32 v213, s12, v68
	v_cndmask_b32_e64 v51, 0, 1.0, vcc
	v_cmp_eq_u32_e32 vcc, 50, v1
	s_add_i32 s12, 0, 0x25a00
	v_xor_b32_e32 v74, 32, v161
	v_cndmask_b32_e64 v52, 0, 1.0, vcc
	v_cmp_eq_u32_e32 vcc, 51, v1
	v_add_u32_e32 v77, 64, v77
	v_add3_u32 v217, s18, v68, v71
	v_cndmask_b32_e64 v53, 0, 1.0, vcc
	v_cmp_eq_u32_e32 vcc, 52, v1
	v_add_u32_e32 v71, s18, v71
	v_lshl_or_b32 v67, v67, 6, v73
	v_cndmask_b32_e64 v54, 0, 1.0, vcc
	v_cmp_eq_u32_e32 vcc, 53, v1
	v_add_u32_e32 v214, s12, v68
	s_add_i32 s12, 0, 0x25b00
	v_cndmask_b32_e64 v55, 0, 1.0, vcc
	v_cmp_eq_u32_e32 vcc, 54, v1
	v_add_u32_e32 v218, v71, v67
	v_sub_u32_e32 v67, 0, v161
	v_cndmask_b32_e64 v56, 0, 1.0, vcc
	v_cmp_eq_u32_e32 vcc, 55, v1
	v_add_u32_e32 v215, s12, v68
	v_add_u32_e32 v219, v71, v68
	v_cndmask_b32_e64 v57, 0, 1.0, vcc
	v_cmp_eq_u32_e32 vcc, 56, v1
	v_cndmask_b32_e64 v220, v67, v161, s[2:3]
	v_mul_u32_u24_e32 v67, 0x90, v161
	v_cndmask_b32_e64 v58, 0, 1.0, vcc
	v_cmp_eq_u32_e32 vcc, 57, v1
	v_mov_b32_e32 v68, v69
	s_mov_b32 s13, 0
	v_cndmask_b32_e64 v59, 0, 1.0, vcc
	v_cmp_eq_u32_e32 vcc, 58, v1
	v_add_u32_e32 v183, s14, v76
	v_add_u32_e32 v184, s16, v76
	v_cndmask_b32_e64 v60, 0, 1.0, vcc
	v_cmp_eq_u32_e32 vcc, 59, v1
	v_add_u32_e32 v185, s20, v76
	v_add_u32_e32 v186, s21, v76
	v_cndmask_b32_e64 v61, 0, 1.0, vcc
	v_cmp_eq_u32_e32 vcc, 60, v1
	v_add_u32_e32 v189, s23, v76
	v_add_u32_e32 v190, s25, v76
	v_cndmask_b32_e64 v62, 0, 1.0, vcc
	v_cmp_eq_u32_e32 vcc, 61, v1
	v_add_u32_e32 v197, s15, v78
	v_add_u32_e32 v199, s17, v78
	v_cndmask_b32_e64 v63, 0, 1.0, vcc
	v_cmp_eq_u32_e32 vcc, 62, v1
	v_add_u32_e32 v201, s19, v78
	v_add_u32_e32 v205, s22, v78
	v_cndmask_b32_e64 v64, 0, 1.0, vcc
	v_cmp_eq_u32_e32 vcc, 63, v1
	v_add_u32_e32 v207, s24, v78
	v_cmp_gt_i32_e64 s[6:7], 8, v161
	v_cndmask_b32_e64 v65, 0, 1.0, vcc
	v_cmp_lt_i32_e32 vcc, v74, v77
	v_add_u32_e32 v221, 0x300, v75
	v_add_u32_e32 v222, 0x500, v76
	v_cndmask_b32_e32 v74, v161, v74, vcc
	v_lshlrev_b32_e32 v216, 2, v74
	v_lshlrev_b32_e32 v223, 1, v66
	v_lshlrev_b32_e32 v224, 1, v70
	v_lshlrev_b32_e32 v225, 1, v72
	s_movk_i32 s19, 0x7fff
	v_add_u32_e32 v226, s18, v67
	v_mov_b64_e32 v[66:67], v[68:69]
	v_mov_b64_e32 v[72:73], v[68:69]
	v_mov_b64_e32 v[70:71], v[68:69]
	v_mov_b64_e32 v[76:77], v[68:69]
	v_mov_b64_e32 v[74:75], v[68:69]
	v_mov_b64_e32 v[80:81], v[68:69]
	v_mov_b64_e32 v[78:79], v[68:69]
	v_mov_b64_e32 v[84:85], v[68:69]
	v_mov_b64_e32 v[82:83], v[68:69]
	v_mov_b64_e32 v[88:89], v[68:69]
	v_mov_b64_e32 v[86:87], v[68:69]
	v_mov_b64_e32 v[92:93], v[68:69]
	v_mov_b64_e32 v[90:91], v[68:69]
	v_mov_b64_e32 v[96:97], v[68:69]
	v_mov_b64_e32 v[94:95], v[68:69]
	v_mov_b64_e32 v[100:101], v[68:69]
	v_mov_b64_e32 v[98:99], v[68:69]
	v_mov_b64_e32 v[104:105], v[68:69]
	v_mov_b64_e32 v[102:103], v[68:69]
	v_mov_b64_e32 v[108:109], v[68:69]
	v_mov_b64_e32 v[106:107], v[68:69]
	v_mov_b64_e32 v[112:113], v[68:69]
	v_mov_b64_e32 v[110:111], v[68:69]
	v_mov_b64_e32 v[116:117], v[68:69]
	v_mov_b64_e32 v[114:115], v[68:69]
	v_mov_b64_e32 v[120:121], v[68:69]
	v_mov_b64_e32 v[118:119], v[68:69]
	v_mov_b64_e32 v[124:125], v[68:69]
	v_mov_b64_e32 v[122:123], v[68:69]
	v_mov_b64_e32 v[128:129], v[68:69]
	v_mov_b64_e32 v[126:127], v[68:69]
	s_mov_b32 s20, 0
	v_and_b32_e32 v130, 31, v1
	v_lshrrev_b32_e32 v131, 5, v1
	v_bfe_u32 v132, v130, 2, 1
	v_lshrrev_b32_e32 v133, 3, v130
	v_and_b32_e32 v134, 3, v130
	v_lshl_add_u32 v133, v133, 2, v134
	v_cmp_eq_u32_e32 vcc, v132, v131
	s_nop 1
	s_nop 1
	v_mov_b32_e32 v134, 0xff
	v_cndmask_b32_e32 v133, v134, v133, vcc
	v_cmp_eq_u32_e64 s[100:101], 0, v133
	v_mov_b32_e32 v18, 0
	v_mov_b32_e32 v34, 0
	v_cndmask_b32_e64 v2, 0, 1.0, s[100:101]
	v_cndmask_b32_e64 v50, 0, 1.0, s[100:101]
	v_cmp_eq_u32_e64 s[100:101], 1, v133
	v_mov_b32_e32 v19, 0
	v_mov_b32_e32 v35, 0
	v_cndmask_b32_e64 v3, 0, 1.0, s[100:101]
	v_cndmask_b32_e64 v51, 0, 1.0, s[100:101]
	v_cmp_eq_u32_e64 s[100:101], 2, v133
	v_mov_b32_e32 v20, 0
	v_mov_b32_e32 v36, 0
	v_cndmask_b32_e64 v4, 0, 1.0, s[100:101]
	v_cndmask_b32_e64 v52, 0, 1.0, s[100:101]
	v_cmp_eq_u32_e64 s[100:101], 3, v133
	v_mov_b32_e32 v21, 0
	v_mov_b32_e32 v37, 0
	v_cndmask_b32_e64 v5, 0, 1.0, s[100:101]
	v_cndmask_b32_e64 v53, 0, 1.0, s[100:101]
	v_cmp_eq_u32_e64 s[100:101], 4, v133
	v_mov_b32_e32 v22, 0
	v_mov_b32_e32 v38, 0
	v_cndmask_b32_e64 v6, 0, 1.0, s[100:101]
	v_cndmask_b32_e64 v54, 0, 1.0, s[100:101]
	v_cmp_eq_u32_e64 s[100:101], 5, v133
	v_mov_b32_e32 v23, 0
	v_mov_b32_e32 v39, 0
	v_cndmask_b32_e64 v7, 0, 1.0, s[100:101]
	v_cndmask_b32_e64 v55, 0, 1.0, s[100:101]
	v_cmp_eq_u32_e64 s[100:101], 6, v133
	v_mov_b32_e32 v24, 0
	v_mov_b32_e32 v40, 0
	v_cndmask_b32_e64 v8, 0, 1.0, s[100:101]
	v_cndmask_b32_e64 v56, 0, 1.0, s[100:101]
	v_cmp_eq_u32_e64 s[100:101], 7, v133
	v_mov_b32_e32 v25, 0
	v_mov_b32_e32 v41, 0
	v_cndmask_b32_e64 v9, 0, 1.0, s[100:101]
	v_cndmask_b32_e64 v57, 0, 1.0, s[100:101]
	v_cmp_eq_u32_e64 s[100:101], 8, v133
	v_mov_b32_e32 v26, 0
	v_mov_b32_e32 v42, 0
	v_cndmask_b32_e64 v10, 0, 1.0, s[100:101]
	v_cndmask_b32_e64 v58, 0, 1.0, s[100:101]
	v_cmp_eq_u32_e64 s[100:101], 9, v133
	v_mov_b32_e32 v27, 0
	v_mov_b32_e32 v43, 0
	v_cndmask_b32_e64 v11, 0, 1.0, s[100:101]
	v_cndmask_b32_e64 v59, 0, 1.0, s[100:101]
	v_cmp_eq_u32_e64 s[100:101], 10, v133
	v_mov_b32_e32 v28, 0
	v_mov_b32_e32 v44, 0
	v_cndmask_b32_e64 v12, 0, 1.0, s[100:101]
	v_cndmask_b32_e64 v60, 0, 1.0, s[100:101]
	v_cmp_eq_u32_e64 s[100:101], 11, v133
	v_mov_b32_e32 v29, 0
	v_mov_b32_e32 v45, 0
	v_cndmask_b32_e64 v13, 0, 1.0, s[100:101]
	v_cndmask_b32_e64 v61, 0, 1.0, s[100:101]
	v_cmp_eq_u32_e64 s[100:101], 12, v133
	v_mov_b32_e32 v30, 0
	v_mov_b32_e32 v46, 0
	v_cndmask_b32_e64 v14, 0, 1.0, s[100:101]
	v_cndmask_b32_e64 v62, 0, 1.0, s[100:101]
	v_cmp_eq_u32_e64 s[100:101], 13, v133
	v_mov_b32_e32 v31, 0
	v_mov_b32_e32 v47, 0
	v_cndmask_b32_e64 v15, 0, 1.0, s[100:101]
	v_cndmask_b32_e64 v63, 0, 1.0, s[100:101]
	v_cmp_eq_u32_e64 s[100:101], 14, v133
	v_mov_b32_e32 v32, 0
	v_mov_b32_e32 v48, 0
	v_cndmask_b32_e64 v16, 0, 1.0, s[100:101]
	v_cndmask_b32_e64 v64, 0, 1.0, s[100:101]
	v_cmp_eq_u32_e64 s[100:101], 15, v133
	v_mov_b32_e32 v33, 0
	v_mov_b32_e32 v49, 0
	v_cndmask_b32_e64 v17, 0, 1.0, s[100:101]
	v_cndmask_b32_e64 v65, 0, 1.0, s[100:101]

.LBB0_362:
	s_add_i32 s12, s21, -7
	s_and_b64 s[22:23], s[2:3], exec
	s_cselect_b32 s15, s21, s12
	s_add_i32 s12, s15, -1
	s_max_i32 s12, s12, s14
	s_min_i32 s12, s12, s17
	s_mulk_i32 s12, 0x1800
	v_lshl_add_u64 v[130:131], v[158:159], 0, s[12:13]
	s_max_i32 s12, s15, s14
	s_min_i32 s12, s12, s17
	s_mulk_i32 s12, 0x1800
	v_lshl_add_u64 v[132:133], v[158:159], 0, s[12:13]
	s_add_i32 s12, s15, 1
	s_max_i32 s12, s12, s14
	s_min_i32 s12, s12, s17
	s_mulk_i32 s12, 0x1800
	v_lshl_add_u64 v[134:135], v[158:159], 0, s[12:13]
	s_add_i32 s12, s15, 2
	s_max_i32 s12, s12, s14
	s_min_i32 s12, s12, s17
	s_mulk_i32 s12, 0x1800
	v_lshl_add_u64 v[136:137], v[158:159], 0, s[12:13]
	s_add_i32 s12, s15, 3
	s_max_i32 s12, s12, s14
	s_min_i32 s12, s12, s17
	s_mulk_i32 s12, 0x1800
	v_lshl_add_u64 v[138:139], v[158:159], 0, s[12:13]
	s_add_i32 s12, s15, 4
	s_max_i32 s12, s12, s14
	s_min_i32 s12, s12, s17
	s_mulk_i32 s12, 0x1800
	v_lshl_add_u64 v[140:141], v[158:159], 0, s[12:13]
	s_add_i32 s12, s15, 5
	s_max_i32 s12, s12, s14
	s_min_i32 s12, s12, s17
	s_mulk_i32 s12, 0x1800
	v_lshl_add_u64 v[142:143], v[158:159], 0, s[12:13]
	s_add_i32 s12, s15, 6
	s_max_i32 s12, s12, s14
	s_min_i32 s12, s12, s17
	s_mulk_i32 s12, 0x1800
	v_lshl_add_u64 v[144:145], v[158:159], 0, s[12:13]
	s_add_i32 s12, s15, 7
	global_load_ushort v236, v[130:131], off
	global_load_ushort v233, v[132:133], off
	global_load_ushort v235, v[134:135], off
	global_load_ushort v232, v[136:137], off
	global_load_ushort v230, v[138:139], off
	global_load_ushort v229, v[140:141], off
	global_load_ushort v228, v[142:143], off
	global_load_ushort v227, v[144:145], off
	s_max_i32 s12, s12, s14
	s_min_i32 s12, s12, s17
	s_mulk_i32 s12, 0x1800
	s_add_i32 s15, s15, 8
	v_lshl_add_u64 v[130:131], v[158:159], 0, s[12:13]
	s_max_i32 s12, s15, s14
	s_min_i32 s12, s12, s17
	s_mulk_i32 s12, 0x1800
	v_lshl_add_u64 v[132:133], v[158:159], 0, s[12:13]
	global_load_ushort v234, v[130:131], off
	global_load_ushort v231, v[132:133], off
	s_waitcnt lgkmcnt(0)
	v_and_b32_e32 v132, 15, v1
	v_lshrrev_b32_e32 v133, 4, v1
	v_lshl_add_u32 v132, v132, 2, v133
	v_lshl_add_u32 v130, v132, 2, s18
	v_lshl_add_u32 v131, v1, 2, s18
	ds_read_b32 v138, v130 offset:768
	ds_read_b32 v139, v130 offset:2304
	ds_read_b32 v140, v130 offset:3840
	ds_read_b32 v141, v130 offset:5376
	ds_read_b32 v142, v130 offset:6912
	ds_read_b32 v143, v130 offset:8448
	ds_read_b32 v144, v130 offset:9984
	ds_read_b32 v145, v130 offset:11520
	v_and_b32_e32 v132, 31, v1
	v_lshrrev_b32_e32 v133, 5, v1
	v_lshlrev_b32_e32 v160, 4, v133
	v_lshlrev_b32_e32 v134, 8, v133
	v_lshl_add_u32 v237, v132, 2, v134
	v_add_u32_e32 v237, 0x100, v237
	v_lshlrev_b32_e32 v135, 2, v132
	v_sub_u32_e32 v255, v135, v134
	v_add_u32_e32 v255, 0x200, v255
	s_mov_b32 s98, 0
	s_mov_b32 s99, -1
	s_waitcnt lgkmcnt(0)
	ds_write_b32 v131, v138 offset:768
	ds_write_b32 v131, v139 offset:2304
	ds_write_b32 v131, v140 offset:3840
	ds_write_b32 v131, v141 offset:5376
	ds_write_b32 v131, v142 offset:6912
	ds_write_b32 v131, v143 offset:8448
	ds_write_b32 v131, v144 offset:9984
	ds_write_b32 v131, v145 offset:11520
	s_waitcnt lgkmcnt(0)
.LBB0_363:
	s_add_i32 s12, s18, s16
	v_add_u32_e32 v253, s12, v160
	v_add_u32_e32 v238, s12, v237
	v_add_u32_e32 v239, s12, v255
	v_xor_b32_e32 v240, 32, v1
	s_add_i32 s100, s12, 0x500
	v_lshl_add_u32 v240, v240, 2, s100
	ds_read_b128 v[130:133], v253 offset:768
	ds_read_b128 v[134:137], v253 offset:800
	ds_read_b128 v[138:141], v253 offset:832
	ds_read_b128 v[142:145], v253 offset:864
	ds_read_b128 v[146:149], v253 offset:896
	ds_read_b128 v[150:153], v253 offset:928
	ds_read_b128 v[154:157], v253 offset:960
	ds_read_b128 v[162:165], v253 offset:992
	ds_read_b32 v252, v240
	ds_read_b32 v248, v238
	ds_read_b32 v249, v238 offset:128
	ds_read_b32 v250, v239
	ds_read_b32 v251, v239 offset:128
	s_waitcnt lgkmcnt(12)
	v_pk_mul_f32 v[166:167], v[2:3], v[130:131]
	v_pk_mul_f32 v[168:169], v[34:35], v[130:131]
	v_pk_mul_f32 v[238:239], v[66:67], v[130:131]
	v_pk_mul_f32 v[240:241], v[98:99], v[130:131]
	v_pk_fma_f32 v[166:167], v[4:5], v[132:133], v[166:167]
	v_pk_fma_f32 v[168:169], v[36:37], v[132:133], v[168:169]
	v_pk_fma_f32 v[238:239], v[68:69], v[132:133], v[238:239]
	v_pk_fma_f32 v[240:241], v[100:101], v[132:133], v[240:241]
	ds_read_b128 v[130:133], v253 offset:0
	s_waitcnt lgkmcnt(12)
	v_pk_fma_f32 v[166:167], v[6:7], v[134:135], v[166:167]
	v_pk_fma_f32 v[168:169], v[38:39], v[134:135], v[168:169]
	v_pk_fma_f32 v[238:239], v[70:71], v[134:135], v[238:239]
	v_pk_fma_f32 v[240:241], v[102:103], v[134:135], v[240:241]
	v_pk_fma_f32 v[166:167], v[8:9], v[136:137], v[166:167]
	v_pk_fma_f32 v[168:169], v[40:41], v[136:137], v[168:169]
	v_pk_fma_f32 v[238:239], v[72:73], v[136:137], v[238:239]
	v_pk_fma_f32 v[240:241], v[104:105], v[136:137], v[240:241]
	ds_read_b128 v[134:137], v253 offset:32
	s_waitcnt lgkmcnt(12)
	v_pk_fma_f32 v[166:167], v[10:11], v[138:139], v[166:167]
	v_pk_fma_f32 v[168:169], v[42:43], v[138:139], v[168:169]
	v_pk_fma_f32 v[238:239], v[74:75], v[138:139], v[238:239]
	v_pk_fma_f32 v[240:241], v[106:107], v[138:139], v[240:241]
	v_pk_fma_f32 v[166:167], v[12:13], v[140:141], v[166:167]
	v_pk_fma_f32 v[168:169], v[44:45], v[140:141], v[168:169]
	v_pk_fma_f32 v[238:239], v[76:77], v[140:141], v[238:239]
	v_pk_fma_f32 v[240:241], v[108:109], v[140:141], v[240:241]
	ds_read_b128 v[138:141], v253 offset:64
	s_waitcnt lgkmcnt(12)
	v_pk_fma_f32 v[166:167], v[14:15], v[142:143], v[166:167]
	v_pk_fma_f32 v[168:169], v[46:47], v[142:143], v[168:169]
	v_pk_fma_f32 v[238:239], v[78:79], v[142:143], v[238:239]
	v_pk_fma_f32 v[240:241], v[110:111], v[142:143], v[240:241]
	v_pk_fma_f32 v[166:167], v[16:17], v[144:145], v[166:167]
	v_pk_fma_f32 v[168:169], v[48:49], v[144:145], v[168:169]
	v_pk_fma_f32 v[238:239], v[80:81], v[144:145], v[238:239]
	v_pk_fma_f32 v[240:241], v[112:113], v[144:145], v[240:241]
	ds_read_b128 v[142:145], v253 offset:96
	s_waitcnt lgkmcnt(12)
	v_pk_fma_f32 v[166:167], v[18:19], v[146:147], v[166:167]
	v_pk_fma_f32 v[168:169], v[50:51], v[146:147], v[168:169]
	v_pk_fma_f32 v[238:239], v[82:83], v[146:147], v[238:239]
	v_pk_fma_f32 v[240:241], v[114:115], v[146:147], v[240:241]
	v_pk_fma_f32 v[166:167], v[20:21], v[148:149], v[166:167]
	v_pk_fma_f32 v[168:169], v[52:53], v[148:149], v[168:169]
	v_pk_fma_f32 v[238:239], v[84:85], v[148:149], v[238:239]
	v_pk_fma_f32 v[240:241], v[116:117], v[148:149], v[240:241]
	ds_read_b128 v[146:149], v253 offset:128
	s_waitcnt lgkmcnt(12)
	v_pk_fma_f32 v[166:167], v[22:23], v[150:151], v[166:167]
	v_pk_fma_f32 v[168:169], v[54:55], v[150:151], v[168:169]
	v_pk_fma_f32 v[238:239], v[86:87], v[150:151], v[238:239]
	v_pk_fma_f32 v[240:241], v[118:119], v[150:151], v[240:241]
	v_pk_fma_f32 v[166:167], v[24:25], v[152:153], v[166:167]
	v_pk_fma_f32 v[168:169], v[56:57], v[152:153], v[168:169]
	v_pk_fma_f32 v[238:239], v[88:89], v[152:153], v[238:239]
	v_pk_fma_f32 v[240:241], v[120:121], v[152:153], v[240:241]
	ds_read_b128 v[150:153], v253 offset:160
	s_waitcnt lgkmcnt(12)
	v_pk_fma_f32 v[166:167], v[26:27], v[154:155], v[166:167]
	v_pk_fma_f32 v[168:169], v[58:59], v[154:155], v[168:169]
	v_pk_fma_f32 v[238:239], v[90:91], v[154:155], v[238:239]
	v_pk_fma_f32 v[240:241], v[122:123], v[154:155], v[240:241]
	v_pk_fma_f32 v[166:167], v[28:29], v[156:157], v[166:167]
	v_pk_fma_f32 v[168:169], v[60:61], v[156:157], v[168:169]
	v_pk_fma_f32 v[238:239], v[92:93], v[156:157], v[238:239]
	v_pk_fma_f32 v[240:241], v[124:125], v[156:157], v[240:241]
	ds_read_b128 v[154:157], v253 offset:192
	s_waitcnt lgkmcnt(12)
	v_pk_fma_f32 v[166:167], v[30:31], v[162:163], v[166:167]
	v_pk_fma_f32 v[168:169], v[62:63], v[162:163], v[168:169]
	v_pk_fma_f32 v[238:239], v[94:95], v[162:163], v[238:239]
	v_pk_fma_f32 v[240:241], v[126:127], v[162:163], v[240:241]
	v_pk_fma_f32 v[166:167], v[32:33], v[164:165], v[166:167]
	v_pk_fma_f32 v[168:169], v[64:65], v[164:165], v[168:169]
	v_pk_fma_f32 v[238:239], v[96:97], v[164:165], v[238:239]
	v_pk_fma_f32 v[240:241], v[128:129], v[164:165], v[240:241]
	ds_read_b128 v[162:165], v253 offset:224
	v_add_f32_e32 v244, v238, v239
	v_add_f32_e32 v245, v240, v241
	v_add_f32_e32 v242, v166, v167
	v_add_f32_e32 v243, v168, v169
	s_nop 1
	v_permlane32_swap_b32_e32 v244, v245
	v_permlane32_swap_b32_e32 v242, v243
	s_nop 0
	v_add_f32_e32 v247, v244, v245
	v_add_f32_e32 v246, v242, v243
	s_waitcnt lgkmcnt(12)
	v_cndmask_b32_e64 v168, -v247, v252, s[98:99]
	v_cndmask_b32_e64 v169, v252, -v247, s[98:99]
	v_cndmask_b32_e64 v166, -v246, 0, s[98:99]
	v_cndmask_b32_e64 v167, 0, -v246, s[98:99]
	s_waitcnt lgkmcnt(4)
	v_pk_mul_f32 v[2:3], v[2:3], v[130:131]
	v_pk_mul_f32 v[4:5], v[4:5], v[132:133]
	v_pk_mul_f32 v[6:7], v[6:7], v[134:135]
	v_pk_mul_f32 v[8:9], v[8:9], v[136:137]
	v_pk_mul_f32 v[10:11], v[10:11], v[138:139]
	v_pk_mul_f32 v[12:13], v[12:13], v[140:141]
	v_pk_mul_f32 v[14:15], v[14:15], v[142:143]
	v_pk_mul_f32 v[16:17], v[16:17], v[144:145]
	s_waitcnt lgkmcnt(4)
	v_pk_mul_f32 v[34:35], v[34:35], v[130:131]
	v_pk_mul_f32 v[36:37], v[36:37], v[132:133]
	v_pk_mul_f32 v[38:39], v[38:39], v[134:135]
	v_pk_mul_f32 v[40:41], v[40:41], v[136:137]
	v_pk_mul_f32 v[42:43], v[42:43], v[138:139]
	v_pk_mul_f32 v[44:45], v[44:45], v[140:141]
	v_pk_mul_f32 v[46:47], v[46:47], v[142:143]
	v_pk_mul_f32 v[48:49], v[48:49], v[144:145]
	s_waitcnt lgkmcnt(8)
	v_mfma_f32_32x32x2_f32 v[2:17], v248, v166, v[2:17]
	s_waitcnt lgkmcnt(4)
	v_pk_mul_f32 v[66:67], v[66:67], v[130:131]
	v_pk_mul_f32 v[68:69], v[68:69], v[132:133]
	v_pk_mul_f32 v[70:71], v[70:71], v[134:135]
	v_pk_mul_f32 v[72:73], v[72:73], v[136:137]
	v_pk_mul_f32 v[74:75], v[74:75], v[138:139]
	v_pk_mul_f32 v[76:77], v[76:77], v[140:141]
	v_pk_mul_f32 v[78:79], v[78:79], v[142:143]
	v_pk_mul_f32 v[80:81], v[80:81], v[144:145]
	v_mfma_f32_32x32x2_f32 v[34:49], v250, v167, v[34:49]
	s_waitcnt lgkmcnt(4)
	v_pk_mul_f32 v[98:99], v[98:99], v[130:131]
	v_pk_mul_f32 v[100:101], v[100:101], v[132:133]
	v_pk_mul_f32 v[102:103], v[102:103], v[134:135]
	v_pk_mul_f32 v[104:105], v[104:105], v[136:137]
	v_pk_mul_f32 v[106:107], v[106:107], v[138:139]
	v_pk_mul_f32 v[108:109], v[108:109], v[140:141]
	v_pk_mul_f32 v[110:111], v[110:111], v[142:143]
	v_pk_mul_f32 v[112:113], v[112:113], v[144:145]
	v_mfma_f32_32x32x2_f32 v[66:81], v248, v168, v[66:81]
	s_waitcnt lgkmcnt(0)
	v_pk_mul_f32 v[18:19], v[18:19], v[146:147]
	v_pk_mul_f32 v[20:21], v[20:21], v[148:149]
	v_pk_mul_f32 v[22:23], v[22:23], v[150:151]
	v_pk_mul_f32 v[24:25], v[24:25], v[152:153]
	v_pk_mul_f32 v[26:27], v[26:27], v[154:155]
	v_pk_mul_f32 v[28:29], v[28:29], v[156:157]
	v_pk_mul_f32 v[30:31], v[30:31], v[162:163]
	v_pk_mul_f32 v[32:33], v[32:33], v[164:165]
	v_mfma_f32_32x32x2_f32 v[98:113], v250, v169, v[98:113]
	s_waitcnt lgkmcnt(0)
	v_pk_mul_f32 v[50:51], v[50:51], v[146:147]
	v_pk_mul_f32 v[52:53], v[52:53], v[148:149]
	v_pk_mul_f32 v[54:55], v[54:55], v[150:151]
	v_pk_mul_f32 v[56:57], v[56:57], v[152:153]
	v_pk_mul_f32 v[58:59], v[58:59], v[154:155]
	v_pk_mul_f32 v[60:61], v[60:61], v[156:157]
	v_pk_mul_f32 v[62:63], v[62:63], v[162:163]
	v_pk_mul_f32 v[64:65], v[64:65], v[164:165]
	v_mfma_f32_32x32x2_f32 v[18:33], v249, v166, v[18:33]
	s_waitcnt lgkmcnt(0)
	v_pk_mul_f32 v[82:83], v[82:83], v[146:147]
	v_pk_mul_f32 v[84:85], v[84:85], v[148:149]
	v_pk_mul_f32 v[86:87], v[86:87], v[150:151]
	v_pk_mul_f32 v[88:89], v[88:89], v[152:153]
	v_pk_mul_f32 v[90:91], v[90:91], v[154:155]
	v_pk_mul_f32 v[92:93], v[92:93], v[156:157]
	v_pk_mul_f32 v[94:95], v[94:95], v[162:163]
	v_pk_mul_f32 v[96:97], v[96:97], v[164:165]
	v_mfma_f32_32x32x2_f32 v[50:65], v251, v167, v[50:65]
	s_waitcnt lgkmcnt(0)
	v_pk_mul_f32 v[114:115], v[114:115], v[146:147]
	v_pk_mul_f32 v[116:117], v[116:117], v[148:149]
	v_pk_mul_f32 v[118:119], v[118:119], v[150:151]
	v_pk_mul_f32 v[120:121], v[120:121], v[152:153]
	v_pk_mul_f32 v[122:123], v[122:123], v[154:155]
	v_pk_mul_f32 v[124:125], v[124:125], v[156:157]
	v_pk_mul_f32 v[126:127], v[126:127], v[162:163]
	v_pk_mul_f32 v[128:129], v[128:129], v[164:165]
	v_mfma_f32_32x32x2_f32 v[82:97], v249, v168, v[82:97]
	s_addk_i32 s16, 0x600
	s_cmpk_eq_i32 s16, 0x3000
	v_mfma_f32_32x32x2_f32 v[114:129], v251, v169, v[114:129]
	s_cbranch_scc0 .LBB0_363
	s_cmp_eq_u32 s20, 26
	s_cbranch_scc0 .LBB0_335
	s_ashr_i32 s1, s0, 31
	s_lshl_b64 s[0:1], s[0:1], 15
	s_add_u32 s0, s88, s0
	s_addc_u32 s1, s89, s1
	v_and_b32_e32 v130, 31, v1
	v_lshrrev_b32_e32 v131, 5, v1
	v_lshlrev_b32_e32 v130, 8, v130
	v_lshl_add_u32 v130, v131, 4, v130
	v_mov_b32_e32 v131, 0
	v_lshl_add_u64 v[130:131], s[0:1], 0, v[130:131]
	s_mov_b64 s[0:1], 0x6180000
	v_lshl_add_u64 v[130:131], v[130:131], 0, s[0:1]
	s_mov_b64 s[0:1], 0x2000
	v_lshl_add_u64 v[132:133], v[130:131], 0, s[0:1]
	v_lshl_add_u64 v[136:137], v[132:133], 0, s[0:1]
	v_lshl_add_u64 v[138:139], v[136:137], 0, s[0:1]
	s_nop 8
	s_nop 8
	global_store_dwordx4 v[130:131], v[2:5], off
	global_store_dwordx4 v[130:131], v[6:9], off offset:32
	global_store_dwordx4 v[130:131], v[10:13], off offset:64
	global_store_dwordx4 v[130:131], v[14:17], off offset:96
	global_store_dwordx4 v[130:131], v[18:21], off offset:128
	global_store_dwordx4 v[130:131], v[22:25], off offset:160
	global_store_dwordx4 v[130:131], v[26:29], off offset:192
	global_store_dwordx4 v[130:131], v[30:33], off offset:224
	global_store_dwordx4 v[132:133], v[34:37], off
	global_store_dwordx4 v[132:133], v[38:41], off offset:32
	global_store_dwordx4 v[132:133], v[42:45], off offset:64
	global_store_dwordx4 v[132:133], v[46:49], off offset:96
	global_store_dwordx4 v[132:133], v[50:53], off offset:128
	global_store_dwordx4 v[132:133], v[54:57], off offset:160
	global_store_dwordx4 v[132:133], v[58:61], off offset:192
	global_store_dwordx4 v[132:133], v[62:65], off offset:224
	global_store_dwordx4 v[136:137], v[66:69], off
	global_store_dwordx4 v[136:137], v[70:73], off offset:32
	global_store_dwordx4 v[136:137], v[74:77], off offset:64
	global_store_dwordx4 v[136:137], v[78:81], off offset:96
	global_store_dwordx4 v[136:137], v[82:85], off offset:128
	global_store_dwordx4 v[136:137], v[86:89], off offset:160
	global_store_dwordx4 v[136:137], v[90:93], off offset:192
	global_store_dwordx4 v[136:137], v[94:97], off offset:224
	global_store_dwordx4 v[138:139], v[98:101], off
	global_store_dwordx4 v[138:139], v[102:105], off offset:32
	global_store_dwordx4 v[138:139], v[106:109], off offset:64
	global_store_dwordx4 v[138:139], v[110:113], off offset:96
	global_store_dwordx4 v[138:139], v[114:117], off offset:128
	global_store_dwordx4 v[138:139], v[118:121], off offset:160
	global_store_dwordx4 v[138:139], v[122:125], off offset:192
	global_store_dwordx4 v[138:139], v[126:129], off offset:224

	.amdhsa_kernel _Z4mega4Args
		.amdhsa_group_segment_fixed_size 0
		.amdhsa_private_segment_fixed_size 0
		.amdhsa_kernarg_size 512
		.amdhsa_user_sgpr_count 2
		.amdhsa_user_sgpr_dispatch_ptr 0
		.amdhsa_user_sgpr_queue_ptr 0
		.amdhsa_user_sgpr_kernarg_segment_ptr 1
		.amdhsa_user_sgpr_dispatch_id 0
		.amdhsa_user_sgpr_kernarg_preload_length 0
		.amdhsa_user_sgpr_kernarg_preload_offset 0
		.amdhsa_user_sgpr_private_segment_size 0
		.amdhsa_uses_dynamic_stack 0
		.amdhsa_enable_private_segment 0
		.amdhsa_system_sgpr_workgroup_id_x 1
		.amdhsa_system_sgpr_workgroup_id_y 0
		.amdhsa_system_sgpr_workgroup_id_z 0
		.amdhsa_system_sgpr_workgroup_info 0
		.amdhsa_system_vgpr_workitem_id 2
		.amdhsa_next_free_vgpr 256
		.amdhsa_next_free_sgpr 102
		.amdhsa_accum_offset 256
		.amdhsa_reserve_vcc 1
		.amdhsa_float_round_mode_32 0
		.amdhsa_float_round_mode_16_64 0
		.amdhsa_float_denorm_mode_32 3
		.amdhsa_float_denorm_mode_16_64 3
		.amdhsa_dx10_clamp 1
		.amdhsa_ieee_mode 1
		.amdhsa_fp16_overflow 0
		.amdhsa_tg_split 0
		.amdhsa_exception_fp_ieee_invalid_op 0
		.amdhsa_exception_fp_denorm_src 0
		.amdhsa_exception_fp_ieee_div_zero 0
		.amdhsa_exception_fp_ieee_overflow 0
		.amdhsa_exception_fp_ieee_underflow 0
		.amdhsa_exception_fp_ieee_inexact 0
		.amdhsa_exception_int_div_zero 0
	.end_amdhsa_kernel

amdhsa.kernels:
  - .agpr_count:     0
    .args:
      - .offset:         0
        .size:           256
        .value_kind:     by_value
      - .offset:         256
        .size:           4
        .value_kind:     hidden_block_count_x
      - .offset:         260
        .size:           4
        .value_kind:     hidden_block_count_y
      - .offset:         264
        .size:           4
        .value_kind:     hidden_block_count_z
      - .offset:         268
        .size:           2
        .value_kind:     hidden_group_size_x
      - .offset:         270
        .size:           2
        .value_kind:     hidden_group_size_y
      - .offset:         272
        .size:           2
        .value_kind:     hidden_group_size_z
      - .offset:         274
        .size:           2
        .value_kind:     hidden_remainder_x
      - .offset:         276
        .size:           2
        .value_kind:     hidden_remainder_y
      - .offset:         278
        .size:           2
        .value_kind:     hidden_remainder_z
      - .offset:         296
        .size:           8
        .value_kind:     hidden_global_offset_x
      - .offset:         304
        .size:           8
        .value_kind:     hidden_global_offset_y
      - .offset:         312
        .size:           8
        .value_kind:     hidden_global_offset_z
      - .offset:         320
        .size:           2
        .value_kind:     hidden_grid_dims
      - .offset:         344
        .size:           8
        .value_kind:     hidden_multigrid_sync_arg
      - .offset:         376
        .size:           4
        .value_kind:     hidden_dynamic_lds_size
    .group_segment_fixed_size: 0
    .kernarg_segment_align: 8
    .kernarg_segment_size: 512
    .language:       OpenCL C
    .language_version:
      - 2
      - 0
    .max_flat_workgroup_size: 512
    .name:           _Z4mega4Args
    .private_segment_fixed_size: 0
    .sgpr_count:     108
    .sgpr_spill_count: 33
    .symbol:         _Z4mega4Args.kd
    .uniform_work_group_size: 1
    .uses_dynamic_stack: false
    .vgpr_count:     256
    .vgpr_spill_count: 0
    .wavefront_size: 64
